# final norm phase: split-K fix-up loads and gain loads issued at the top of their blocks (fewer serialized round trips in the last phase)
# speedup vs baseline: 1.0002x; 1.0002x over previous
.LBB0_1230:
	global_load_dwordx4 v[0:3], v[52:53], off nt
	global_load_dwordx4 v[4:7], v[52:53], off offset:1024 nt
	global_load_dwordx4 v[8:11], v[52:53], off offset:2048 nt
	global_load_dwordx4 v[12:15], v[52:53], off offset:3072 nt
	s_cmpk_lt_i32 s2, 0x2000
	s_waitcnt vmcnt(0)
	v_and_b32_e32 v85, 0xffff0000, v0
	v_lshlrev_b32_e32 v84, 16, v0
	v_and_b32_e32 v87, 0xffff0000, v1
	v_lshlrev_b32_e32 v86, 16, v1
	v_and_b32_e32 v81, 0xffff0000, v2
	v_lshlrev_b32_e32 v80, 16, v2
	v_and_b32_e32 v83, 0xffff0000, v3
	v_lshlrev_b32_e32 v82, 16, v3
	v_lshlrev_b32_e32 v76, 16, v4
	v_and_b32_e32 v77, 0xffff0000, v4
	v_lshlrev_b32_e32 v78, 16, v5
	v_and_b32_e32 v79, 0xffff0000, v5
	v_lshlrev_b32_e32 v72, 16, v6
	v_and_b32_e32 v73, 0xffff0000, v6
	v_lshlrev_b32_e32 v74, 16, v7
	v_and_b32_e32 v75, 0xffff0000, v7
	v_lshlrev_b32_e32 v68, 16, v8
	v_and_b32_e32 v69, 0xffff0000, v8
	v_lshlrev_b32_e32 v70, 16, v9
	v_and_b32_e32 v71, 0xffff0000, v9
	v_lshlrev_b32_e32 v64, 16, v10
	v_and_b32_e32 v65, 0xffff0000, v10
	v_lshlrev_b32_e32 v66, 16, v11
	v_and_b32_e32 v67, 0xffff0000, v11
	v_lshlrev_b32_e32 v56, 16, v12
	v_and_b32_e32 v57, 0xffff0000, v12
	v_lshlrev_b32_e32 v60, 16, v13
	v_and_b32_e32 v61, 0xffff0000, v13
	v_lshlrev_b32_e32 v58, 16, v14
	v_and_b32_e32 v59, 0xffff0000, v14
	v_lshlrev_b32_e32 v62, 16, v15
	v_and_b32_e32 v63, 0xffff0000, v15
	s_cbranch_scc1 .LBB0_1229
	s_add_i32 s0, s2, 0xffffe000
	s_lshl_b64 s[6:7], s[0:1], 12
	v_lshl_add_u64 v[88:89], v[50:51], 0, s[6:7]
	global_load_dwordx4 v[4:7], v[88:89], off nt
	global_load_dwordx4 v[0:3], v[88:89], off offset:1024 nt
	v_add_co_u32_e32 v90, vcc, s3, v88
	s_nop 0
	s_nop 0
	v_addc_co_u32_e32 v91, vcc, 0, v89, vcc
	global_load_dwordx4 v[20:23], v[90:91], off nt
	v_add_co_u32_e32 v92, vcc, s10, v88
	s_nop 0
	s_nop 0
	v_addc_co_u32_e32 v93, vcc, 0, v89, vcc
	global_load_dwordx4 v[8:11], v[92:93], off nt
	v_add_co_u32_e32 v94, vcc, s11, v88
	s_nop 0
	s_nop 0
	v_addc_co_u32_e32 v95, vcc, 0, v89, vcc
	global_load_dwordx4 v[100:103], v[94:95], off nt
	s_lshr_b32 s0, s0, 10
	s_add_i32 s0, s0, 1
	s_mul_hi_u32 s7, s0, 0xc000
	s_mul_i32 s0, s0, 0xc000
	s_add_u32 s6, s8, s0
	s_addc_u32 s7, s9, s7
	global_load_dwordx4 v[104:107], v96, s[6:7]
	global_load_dwordx4 v[108:111], v96, s[6:7] offset:16
	global_load_dwordx4 v[24:27], v[90:91], off offset:1024 nt
	global_load_dwordx4 v[16:19], v[92:93], off offset:1024 nt
	global_load_dwordx4 v[12:15], v[94:95], off offset:1024 nt
	global_load_dwordx4 v[32:35], v96, s[6:7] offset:2048
	global_load_dwordx4 v[28:31], v[88:89], off offset:2048 nt
	global_load_dwordx4 v[36:39], v[90:91], off offset:2048 nt
	global_load_dwordx4 v[112:115], v96, s[6:7] offset:2064
	global_load_dwordx4 v[40:43], v[92:93], off offset:2048 nt
	global_load_dwordx4 v[116:119], v97, s[6:7]
	global_load_dwordx4 v[120:123], v[94:95], off offset:2048 nt
	global_load_dwordx4 v[136:139], v97, s[6:7] offset:16
	global_load_dwordx4 v[140:143], v[88:89], off offset:3072 nt
	global_load_dwordx4 v[144:147], v[90:91], off offset:3072 nt
	global_load_dwordx4 v[148:151], v[92:93], off offset:3072 nt
	global_load_dwordx4 v[152:155], v98, s[6:7] offset:16
	global_load_dwordx4 v[156:159], v[94:95], off offset:3072 nt
	global_load_dwordx4 v[160:163], v98, s[6:7]
	s_nop 0
	s_nop 0
	s_nop 0
	s_nop 0
	s_nop 0
	s_nop 0
	s_nop 0
	s_nop 0
	s_nop 0
	s_nop 0
	s_nop 0
	s_waitcnt vmcnt(24)
	s_waitcnt vmcnt(23)
	v_and_b32_e32 v125, 0xffff0000, v4
	v_lshlrev_b32_e32 v124, 16, v4
	v_and_b32_e32 v127, 0xffff0000, v5
	v_lshlrev_b32_e32 v126, 16, v5
	v_and_b32_e32 v5, 0xffff0000, v6
	v_lshlrev_b32_e32 v4, 16, v6
	v_and_b32_e32 v129, 0xffff0000, v7
	v_lshlrev_b32_e32 v128, 16, v7
	s_waitcnt vmcnt(21)
	v_and_b32_e32 v131, 0xffff0000, v20
	v_lshlrev_b32_e32 v130, 16, v20
	v_and_b32_e32 v133, 0xffff0000, v21
	v_lshlrev_b32_e32 v132, 16, v21
	v_and_b32_e32 v21, 0xffff0000, v22
	v_lshlrev_b32_e32 v20, 16, v22
	v_and_b32_e32 v135, 0xffff0000, v23
	v_lshlrev_b32_e32 v134, 16, v23
	v_pk_add_f32 v[22:23], v[124:125], v[130:131]
	v_pk_add_f32 v[124:125], v[126:127], v[132:133]
	s_waitcnt vmcnt(20)
	v_and_b32_e32 v127, 0xffff0000, v8
	v_lshlrev_b32_e32 v126, 16, v8
	v_and_b32_e32 v131, 0xffff0000, v9
	v_lshlrev_b32_e32 v130, 16, v9
	v_and_b32_e32 v9, 0xffff0000, v10
	v_lshlrev_b32_e32 v8, 16, v10
	v_and_b32_e32 v133, 0xffff0000, v11
	v_lshlrev_b32_e32 v132, 16, v11
	v_pk_add_f32 v[4:5], v[4:5], v[20:21]
	v_pk_add_f32 v[10:11], v[128:129], v[134:135]
	s_waitcnt vmcnt(19)
	v_and_b32_e32 v21, 0xffff0000, v100
	v_lshlrev_b32_e32 v20, 16, v100
	v_and_b32_e32 v129, 0xffff0000, v101
	v_lshlrev_b32_e32 v128, 16, v101
	v_and_b32_e32 v101, 0xffff0000, v102
	v_lshlrev_b32_e32 v100, 16, v102
	v_and_b32_e32 v135, 0xffff0000, v103
	v_lshlrev_b32_e32 v134, 16, v103
	v_pk_add_f32 v[8:9], v[8:9], v[100:101]
	v_pk_add_f32 v[100:101], v[132:133], v[134:135]
	v_pk_add_f32 v[4:5], v[4:5], v[8:9]
	v_lshlrev_b32_e32 v6, 16, v0
	v_and_b32_e32 v7, 0xffff0000, v0
	v_pk_add_f32 v[8:9], v[10:11], v[100:101]
	s_waitcnt vmcnt(17)
	v_pk_fma_f32 v[80:81], v[108:109], v[4:5], v[80:81]
	s_waitcnt vmcnt(16)
	v_lshlrev_b32_e32 v4, 16, v24
	v_and_b32_e32 v5, 0xffff0000, v24
	v_pk_fma_f32 v[82:83], v[110:111], v[8:9], v[82:83]
	s_waitcnt vmcnt(15)
	v_lshlrev_b32_e32 v8, 16, v16
	v_and_b32_e32 v9, 0xffff0000, v16
	v_pk_add_f32 v[4:5], v[6:7], v[4:5]
	s_waitcnt vmcnt(14)
	v_lshlrev_b32_e32 v6, 16, v12
	v_and_b32_e32 v7, 0xffff0000, v12
	v_pk_add_f32 v[6:7], v[8:9], v[6:7]
	v_lshlrev_b32_e32 v0, 16, v1
	v_and_b32_e32 v1, 0xffff0000, v1
	v_lshlrev_b32_e32 v8, 16, v25
	v_and_b32_e32 v9, 0xffff0000, v25
	v_lshlrev_b32_e32 v10, 16, v17
	v_and_b32_e32 v11, 0xffff0000, v17
	v_pk_add_f32 v[0:1], v[0:1], v[8:9]
	v_lshlrev_b32_e32 v8, 16, v13
	v_and_b32_e32 v9, 0xffff0000, v13
	v_pk_add_f32 v[12:13], v[10:11], v[8:9]
	v_lshlrev_b32_e32 v24, 16, v18
	v_pk_add_f32 v[0:1], v[0:1], v[12:13]
	v_lshlrev_b32_e32 v12, 16, v26
	s_waitcnt vmcnt(13)
	v_pk_fma_f32 v[78:79], v[34:35], v[0:1], v[78:79]
	v_lshlrev_b32_e32 v0, 16, v2
	v_and_b32_e32 v1, 0xffff0000, v2
	v_and_b32_e32 v13, 0xffff0000, v26
	v_and_b32_e32 v25, 0xffff0000, v18
	v_pk_add_f32 v[0:1], v[0:1], v[12:13]
	v_lshlrev_b32_e32 v12, 16, v14
	v_and_b32_e32 v13, 0xffff0000, v14
	v_pk_add_f32 v[12:13], v[24:25], v[12:13]
	v_pk_add_f32 v[4:5], v[4:5], v[6:7]
	v_lshlrev_b32_e32 v2, 16, v3
	v_and_b32_e32 v3, 0xffff0000, v3
	v_lshlrev_b32_e32 v16, 16, v27
	v_and_b32_e32 v17, 0xffff0000, v27
	v_lshlrev_b32_e32 v18, 16, v19
	v_and_b32_e32 v19, 0xffff0000, v19
	v_pk_add_f32 v[0:1], v[0:1], v[12:13]
	v_lshlrev_b32_e32 v12, 16, v15
	v_and_b32_e32 v13, 0xffff0000, v15
	v_pk_add_f32 v[20:21], v[126:127], v[20:21]
	v_pk_add_f32 v[102:103], v[130:131], v[128:129]
	v_pk_fma_f32 v[76:77], v[32:33], v[4:5], v[76:77]
	s_nop 0
	s_waitcnt vmcnt(10)
	v_pk_fma_f32 v[72:73], v[112:113], v[0:1], v[72:73]
	v_pk_add_f32 v[0:1], v[2:3], v[16:17]
	v_pk_add_f32 v[2:3], v[18:19], v[12:13]
	v_pk_add_f32 v[20:21], v[22:23], v[20:21]
	v_pk_add_f32 v[22:23], v[124:125], v[102:103]
	v_pk_add_f32 v[0:1], v[0:1], v[2:3]
	v_pk_fma_f32 v[84:85], v[104:105], v[20:21], v[84:85]
	v_pk_fma_f32 v[86:87], v[106:107], v[22:23], v[86:87]
	s_nop 0
	s_nop 0
	s_nop 0
	v_pk_fma_f32 v[74:75], v[114:115], v[0:1], v[74:75]
	s_nop 0
	s_nop 0
	v_lshlrev_b32_e32 v12, 16, v28
	s_nop 0
	v_and_b32_e32 v13, 0xffff0000, v28
	v_lshlrev_b32_e32 v14, 16, v36
	v_and_b32_e32 v15, 0xffff0000, v36
	s_waitcnt vmcnt(9)
	v_lshlrev_b32_e32 v16, 16, v40
	v_and_b32_e32 v17, 0xffff0000, v40
	v_pk_add_f32 v[12:13], v[12:13], v[14:15]
	s_waitcnt vmcnt(7)
	v_lshlrev_b32_e32 v14, 16, v120
	v_and_b32_e32 v15, 0xffff0000, v120
	v_pk_add_f32 v[14:15], v[16:17], v[14:15]
	v_lshlrev_b32_e32 v16, 16, v121
	v_pk_add_f32 v[12:13], v[12:13], v[14:15]
	v_lshlrev_b32_e32 v14, 16, v37
	v_pk_fma_f32 v[68:69], v[116:117], v[12:13], v[68:69]
	v_lshlrev_b32_e32 v12, 16, v29
	v_and_b32_e32 v13, 0xffff0000, v29
	v_and_b32_e32 v15, 0xffff0000, v37
	v_pk_add_f32 v[12:13], v[12:13], v[14:15]
	v_lshlrev_b32_e32 v14, 16, v41
	v_and_b32_e32 v15, 0xffff0000, v41
	v_and_b32_e32 v17, 0xffff0000, v121
	v_pk_add_f32 v[14:15], v[14:15], v[16:17]
	v_lshlrev_b32_e32 v24, 16, v42
	v_pk_add_f32 v[12:13], v[12:13], v[14:15]
	v_lshlrev_b32_e32 v14, 16, v38
	v_pk_fma_f32 v[70:71], v[118:119], v[12:13], v[70:71]
	v_lshlrev_b32_e32 v12, 16, v30
	v_and_b32_e32 v13, 0xffff0000, v30
	v_and_b32_e32 v15, 0xffff0000, v38
	v_and_b32_e32 v25, 0xffff0000, v42
	v_pk_add_f32 v[12:13], v[12:13], v[14:15]
	v_lshlrev_b32_e32 v14, 16, v122
	v_and_b32_e32 v15, 0xffff0000, v122
	v_pk_add_f32 v[14:15], v[24:25], v[14:15]
	v_lshlrev_b32_e32 v16, 16, v31
	v_and_b32_e32 v17, 0xffff0000, v31
	v_lshlrev_b32_e32 v18, 16, v39
	v_and_b32_e32 v19, 0xffff0000, v39
	v_lshlrev_b32_e32 v24, 16, v43
	v_and_b32_e32 v25, 0xffff0000, v43
	v_pk_add_f32 v[12:13], v[12:13], v[14:15]
	v_lshlrev_b32_e32 v14, 16, v123
	v_and_b32_e32 v15, 0xffff0000, v123
	s_waitcnt vmcnt(6)
	v_pk_fma_f32 v[64:65], v[136:137], v[12:13], v[64:65]
	v_pk_add_f32 v[4:5], v[16:17], v[18:19]
	v_pk_add_f32 v[12:13], v[24:25], v[14:15]
	s_waitcnt vmcnt(1)
	v_lshlrev_b32_e32 v14, 16, v156
	v_pk_add_f32 v[4:5], v[4:5], v[12:13]
	v_lshlrev_b32_e32 v12, 16, v148
	v_pk_fma_f32 v[66:67], v[138:139], v[4:5], v[66:67]
	v_lshlrev_b32_e32 v4, 16, v140
	v_and_b32_e32 v5, 0xffff0000, v140
	v_lshlrev_b32_e32 v6, 16, v144
	v_and_b32_e32 v7, 0xffff0000, v144
	v_and_b32_e32 v13, 0xffff0000, v148
	v_and_b32_e32 v15, 0xffff0000, v156
	v_pk_add_f32 v[4:5], v[4:5], v[6:7]
	v_pk_add_f32 v[6:7], v[12:13], v[14:15]
	v_lshlrev_b32_e32 v8, 16, v149
	v_pk_add_f32 v[4:5], v[4:5], v[6:7]
	v_lshlrev_b32_e32 v6, 16, v145
	s_waitcnt vmcnt(0)
	v_pk_fma_f32 v[56:57], v[160:161], v[4:5], v[56:57]
	v_lshlrev_b32_e32 v4, 16, v141
	v_and_b32_e32 v5, 0xffff0000, v141
	v_and_b32_e32 v7, 0xffff0000, v145
	v_and_b32_e32 v9, 0xffff0000, v149
	v_lshlrev_b32_e32 v12, 16, v157
	v_and_b32_e32 v13, 0xffff0000, v157
	v_pk_add_f32 v[4:5], v[4:5], v[6:7]
	v_pk_add_f32 v[6:7], v[8:9], v[12:13]
	v_lshlrev_b32_e32 v8, 16, v150
	v_pk_add_f32 v[4:5], v[4:5], v[6:7]
	v_lshlrev_b32_e32 v6, 16, v146
	v_pk_fma_f32 v[60:61], v[162:163], v[4:5], v[60:61]
	v_lshlrev_b32_e32 v4, 16, v142
	v_and_b32_e32 v5, 0xffff0000, v142
	v_and_b32_e32 v7, 0xffff0000, v146
	v_and_b32_e32 v9, 0xffff0000, v150
	v_lshlrev_b32_e32 v12, 16, v158
	v_and_b32_e32 v13, 0xffff0000, v158
	v_pk_add_f32 v[4:5], v[4:5], v[6:7]
	v_pk_add_f32 v[6:7], v[8:9], v[12:13]
	v_lshlrev_b32_e32 v8, 16, v159
	v_pk_add_f32 v[4:5], v[4:5], v[6:7]
	v_lshlrev_b32_e32 v6, 16, v151
	v_pk_fma_f32 v[58:59], v[152:153], v[4:5], v[58:59]
	v_lshlrev_b32_e32 v0, 16, v143
	v_and_b32_e32 v1, 0xffff0000, v143
	v_lshlrev_b32_e32 v4, 16, v147
	v_and_b32_e32 v5, 0xffff0000, v147
	v_and_b32_e32 v7, 0xffff0000, v151
	v_and_b32_e32 v9, 0xffff0000, v159
	v_pk_add_f32 v[0:1], v[0:1], v[4:5]
	v_pk_add_f32 v[4:5], v[6:7], v[8:9]
	s_nop 0
	v_pk_add_f32 v[0:1], v[0:1], v[4:5]
	s_nop 0
	v_pk_fma_f32 v[62:63], v[154:155], v[0:1], v[62:63]
	s_branch .LBB0_1229
